# P5 epilogue: all residual loads of the 8 row groups issued up front into spare VGPRs (was a load/wait/store ladder); per-group counted waits
# baseline (speedup 1.0000x reference)
.LBB0_548:
	v_lshl_add_u32 v142, s50, 8, v144
	v_lshl_or_b32 v140, s12, 8, v146
	v_ashrrev_i32_e32 v143, 31, v142
	v_ashrrev_i32_e32 v141, 31, v140
	v_lshlrev_b64 v[152:153], 11, v[142:143]
	v_lshl_add_u64 v[152:153], v[152:153], 0, v[140:141]
	v_lshlrev_b64 v[152:153], 1, v[152:153]
	v_lshl_add_u64 v[154:155], s[18:19], 0, v[152:153]
	v_mov_b64_e32 v[238:239], v[154:155]
	s_mov_b32 s99, 0
	global_load_dwordx2 v[156:157], v[154:155], off
	global_load_dwordx2 v[158:159], v[154:155], off offset:32
	global_load_dwordx2 v[160:161], v[154:155], off offset:256
	s_nop 0
	global_load_dwordx2 v[154:155], v[154:155], off offset:288
	s_mov_b32 s98, 0x10000
	v_lshl_add_u64 v[236:237], v[238:239], 0, s[98:99]
	global_load_dwordx2 v[128:129], v[236:237], off
	global_load_dwordx2 v[130:131], v[236:237], off offset:32
	global_load_dwordx2 v[132:133], v[236:237], off offset:256
	global_load_dwordx2 v[134:135], v[236:237], off offset:288
	s_mov_b32 s98, 0x20000
	v_lshl_add_u64 v[236:237], v[238:239], 0, s[98:99]
	global_load_dwordx2 v[214:215], v[236:237], off
	global_load_dwordx2 v[216:217], v[236:237], off offset:32
	global_load_dwordx2 v[218:219], v[236:237], off offset:256
	global_load_dwordx2 v[220:221], v[236:237], off offset:288
	s_mov_b32 s98, 0x30000
	v_lshl_add_u64 v[236:237], v[238:239], 0, s[98:99]
	global_load_dwordx2 v[222:223], v[236:237], off
	global_load_dwordx2 v[224:225], v[236:237], off offset:32
	global_load_dwordx2 v[226:227], v[236:237], off offset:256
	global_load_dwordx2 v[228:229], v[236:237], off offset:288
	s_mov_b32 s98, 0x80000
	v_lshl_add_u64 v[236:237], v[238:239], 0, s[98:99]
	global_load_dwordx2 v[230:231], v[236:237], off
	global_load_dwordx2 v[232:233], v[236:237], off offset:32
	global_load_dwordx2 v[234:235], v[236:237], off offset:256
	global_load_dwordx2 v[136:137], v[236:237], off offset:288
	s_mov_b32 s98, 0x90000
	v_lshl_add_u64 v[236:237], v[238:239], 0, s[98:99]
	global_load_dwordx2 v[240:241], v[236:237], off
	global_load_dwordx2 v[242:243], v[236:237], off offset:32
	global_load_dwordx2 v[244:245], v[236:237], off offset:256
	global_load_dwordx2 v[246:247], v[236:237], off offset:288
	s_mov_b32 s98, 0xa0000
	v_lshl_add_u64 v[236:237], v[238:239], 0, s[98:99]
	global_load_dwordx2 v[248:249], v[236:237], off
	global_load_dwordx2 v[250:251], v[236:237], off offset:32
	global_load_dwordx2 v[252:253], v[236:237], off offset:256
	global_load_dwordx2 v[254:255], v[236:237], off offset:288
	v_and_b32_e32 v162, 64, v150
	v_xor_b32_e32 v151, 16, v150
	v_add_u32_e32 v162, 64, v162
	v_xor_b32_e32 v163, 32, v150
	v_cmp_lt_i32_e32 vcc, v151, v162
	v_lshl_add_u64 v[152:153], s[10:11], 0, v[152:153]
	s_lshl_b32 s50, s12, 2
	v_cndmask_b32_e32 v151, v150, v151, vcc
	v_cmp_lt_i32_e32 vcc, v163, v162
	v_lshlrev_b32_e32 v151, 2, v151
	s_ashr_i32 s51, s50, 31
	v_cndmask_b32_e32 v170, v150, v163, vcc
	s_waitcnt vmcnt(24)
	v_lshlrev_b32_e32 v162, 16, v156
	v_and_b32_e32 v163, 0xffff0000, v156
	v_lshlrev_b32_e32 v156, 16, v157
	v_and_b32_e32 v157, 0xffff0000, v157
	v_lshlrev_b32_e32 v164, 16, v158
	v_and_b32_e32 v165, 0xffff0000, v158
	v_lshlrev_b32_e32 v158, 16, v159
	v_and_b32_e32 v159, 0xffff0000, v159
	v_lshlrev_b32_e32 v166, 16, v160
	v_and_b32_e32 v167, 0xffff0000, v160
	v_lshlrev_b32_e32 v160, 16, v161
	v_and_b32_e32 v161, 0xffff0000, v161
	v_lshlrev_b32_e32 v168, 16, v154
	v_and_b32_e32 v169, 0xffff0000, v154
	v_lshlrev_b32_e32 v154, 16, v155
	v_and_b32_e32 v155, 0xffff0000, v155
	v_pk_add_f32 v[126:127], v[126:127], v[156:157]
	v_pk_add_f32 v[124:125], v[124:125], v[162:163]
	v_pk_add_f32 v[122:123], v[122:123], v[158:159]
	v_pk_add_f32 v[120:121], v[120:121], v[164:165]
	v_pk_add_f32 v[118:119], v[118:119], v[160:161]
	v_pk_add_f32 v[116:117], v[116:117], v[166:167]
	v_pk_add_f32 v[154:155], v[114:115], v[154:155]
	v_pk_add_f32 v[156:157], v[112:113], v[168:169]
	v_mul_f32_e32 v114, v125, v125
	v_mul_f32_e32 v115, v127, v127
	v_cvt_pk_bf16_f32 v112, v124, v125
	v_cvt_pk_bf16_f32 v113, v126, v127
	v_mul_f32_e32 v125, v121, v121
	v_mul_f32_e32 v127, v123, v123
	v_mul_f32_e32 v158, v117, v117
	v_mul_f32_e32 v159, v119, v119
	v_fmac_f32_e32 v114, v124, v124
	v_fmac_f32_e32 v115, v126, v126
	v_fmac_f32_e32 v125, v120, v120
	v_fmac_f32_e32 v127, v122, v122
	v_mul_f32_e32 v160, v157, v157
	v_mul_f32_e32 v161, v155, v155
	global_store_dwordx2 v[152:153], v[112:113], off
	v_fmac_f32_e32 v158, v116, v116
	v_fmac_f32_e32 v159, v118, v118
	v_add_f32_e32 v113, v114, v115
	v_add_f32_e32 v114, v125, v127
	v_fmac_f32_e32 v160, v156, v156
	v_fmac_f32_e32 v161, v154, v154
	v_add_f32_e32 v115, v158, v159
	v_add_f32_e32 v113, v113, v114
	v_cvt_pk_bf16_f32 v112, v120, v121
	v_add_f32_e32 v120, v160, v161
	v_add_f32_e32 v113, v113, v115
	v_add_f32_e32 v114, v113, v120
	ds_bpermute_b32 v115, v151, v114
	v_cvt_pk_bf16_f32 v113, v122, v123
	global_store_dwordx2 v[152:153], v[112:113], off offset:32
	v_cvt_pk_bf16_f32 v116, v116, v117
	v_cvt_pk_bf16_f32 v117, v118, v119
	s_waitcnt lgkmcnt(0)
	v_add_f32_e32 v112, v114, v115
	v_lshlrev_b32_e32 v114, 2, v170
	ds_bpermute_b32 v113, v114, v112
	global_store_dwordx2 v[152:153], v[116:117], off offset:256
	v_cvt_pk_bf16_f32 v116, v156, v157
	v_cvt_pk_bf16_f32 v117, v154, v155
	global_store_dwordx2 v[152:153], v[116:117], off offset:288
	s_and_saveexec_b64 s[54:55], s[0:1]
	s_cbranch_execz .LBB0_550
	v_lshlrev_b64 v[116:117], 7, v[142:143]
	v_lshl_add_u64 v[116:117], s[26:27], 0, v[116:117]
	v_lshl_add_u64 v[116:117], s[50:51], 2, v[116:117]
	s_lshl_b32 s12, s64, 2
	v_lshl_add_u64 v[116:117], v[116:117], 0, s[12:13]
	s_waitcnt lgkmcnt(0)
	v_add_f32_e32 v112, v112, v113
	global_store_dword v[116:117], v112, off
.LBB0_550:
	s_or_b64 exec, exec, s[54:55]
	v_or_b32_e32 v112, 16, v142
	s_waitcnt lgkmcnt(0)
	v_ashrrev_i32_e32 v113, 31, v112
	v_lshlrev_b64 v[116:117], 11, v[112:113]
	v_lshl_add_u64 v[116:117], v[116:117], 0, v[140:141]
	v_lshlrev_b64 v[116:117], 1, v[116:117]
	v_lshl_add_u64 v[118:119], s[18:19], 0, v[116:117]
	v_lshl_add_u64 v[116:117], s[10:11], 0, v[116:117]
	s_waitcnt vmcnt(24)
	v_lshlrev_b32_e32 v126, 16, v128
	v_and_b32_e32 v127, 0xffff0000, v128
	v_lshlrev_b32_e32 v120, 16, v129
	v_and_b32_e32 v121, 0xffff0000, v129
	v_lshlrev_b32_e32 v152, 16, v130
	v_and_b32_e32 v153, 0xffff0000, v130
	v_lshlrev_b32_e32 v122, 16, v131
	v_and_b32_e32 v123, 0xffff0000, v131
	v_lshlrev_b32_e32 v154, 16, v132
	v_and_b32_e32 v155, 0xffff0000, v132
	v_lshlrev_b32_e32 v124, 16, v133
	v_and_b32_e32 v125, 0xffff0000, v133
	v_lshlrev_b32_e32 v156, 16, v134
	v_and_b32_e32 v157, 0xffff0000, v134
	v_lshlrev_b32_e32 v118, 16, v135
	v_and_b32_e32 v119, 0xffff0000, v135
	v_pk_add_f32 v[110:111], v[110:111], v[120:121]
	v_pk_add_f32 v[108:109], v[108:109], v[126:127]
	v_pk_add_f32 v[106:107], v[106:107], v[122:123]
	v_pk_add_f32 v[104:105], v[104:105], v[152:153]
	v_pk_add_f32 v[102:103], v[102:103], v[124:125]
	v_pk_add_f32 v[100:101], v[100:101], v[154:155]
	v_pk_add_f32 v[98:99], v[98:99], v[118:119]
	v_pk_add_f32 v[118:119], v[96:97], v[156:157]
	v_mul_f32_e32 v115, v109, v109
	v_mul_f32_e32 v120, v111, v111
	v_cvt_pk_bf16_f32 v96, v108, v109
	v_cvt_pk_bf16_f32 v97, v110, v111
	v_mul_f32_e32 v109, v105, v105
	v_mul_f32_e32 v111, v107, v107
	v_mul_f32_e32 v121, v101, v101
	v_mul_f32_e32 v122, v103, v103
	v_fmac_f32_e32 v115, v108, v108
	v_fmac_f32_e32 v120, v110, v110
	v_fmac_f32_e32 v109, v104, v104
	v_fmac_f32_e32 v111, v106, v106
	v_mul_f32_e32 v123, v119, v119
	v_mul_f32_e32 v124, v99, v99
	global_store_dwordx2 v[116:117], v[96:97], off
	v_cvt_pk_bf16_f32 v96, v104, v105
	v_fmac_f32_e32 v121, v100, v100
	v_fmac_f32_e32 v122, v102, v102
	v_add_f32_e32 v97, v115, v120
	v_add_f32_e32 v104, v109, v111
	v_fmac_f32_e32 v123, v118, v118
	v_fmac_f32_e32 v124, v98, v98
	v_add_f32_e32 v105, v121, v122
	v_add_f32_e32 v97, v97, v104
	v_add_f32_e32 v97, v97, v105
	v_add_f32_e32 v104, v123, v124
	v_add_f32_e32 v104, v97, v104
	ds_bpermute_b32 v105, v151, v104
	v_cvt_pk_bf16_f32 v97, v106, v107
	global_store_dwordx2 v[116:117], v[96:97], off offset:32
	v_cvt_pk_bf16_f32 v100, v100, v101
	v_cvt_pk_bf16_f32 v101, v102, v103
	s_waitcnt lgkmcnt(0)
	v_add_f32_e32 v96, v104, v105
	ds_bpermute_b32 v97, v114, v96
	global_store_dwordx2 v[116:117], v[100:101], off offset:256
	v_cvt_pk_bf16_f32 v100, v118, v119
	v_cvt_pk_bf16_f32 v101, v98, v99
	global_store_dwordx2 v[116:117], v[100:101], off offset:288
	s_and_saveexec_b64 s[54:55], s[0:1]
	s_cbranch_execz .LBB0_552
	v_lshlrev_b64 v[98:99], 7, v[112:113]
	v_lshl_add_u64 v[98:99], s[26:27], 0, v[98:99]
	v_lshl_add_u64 v[98:99], s[50:51], 2, v[98:99]
	s_lshl_b32 s12, s64, 2
	v_lshl_add_u64 v[98:99], v[98:99], 0, s[12:13]
	s_waitcnt lgkmcnt(0)
	v_add_f32_e32 v96, v96, v97
	global_store_dword v[98:99], v96, off
.LBB0_552:
	s_or_b64 exec, exec, s[54:55]
	v_or_b32_e32 v96, 32, v142
	s_waitcnt lgkmcnt(0)
	v_ashrrev_i32_e32 v97, 31, v96
	v_lshlrev_b64 v[98:99], 11, v[96:97]
	v_lshl_add_u64 v[98:99], v[98:99], 0, v[140:141]
	v_lshlrev_b64 v[98:99], 1, v[98:99]
	v_lshl_add_u64 v[100:101], s[18:19], 0, v[98:99]
	s_mov_b32 s98, 0xb0000
	v_lshl_add_u64 v[236:237], v[238:239], 0, s[98:99]
	global_load_dwordx2 v[128:129], v[236:237], off
	global_load_dwordx2 v[130:131], v[236:237], off offset:32
	global_load_dwordx2 v[132:133], v[236:237], off offset:256
	global_load_dwordx2 v[134:135], v[236:237], off offset:288
	v_lshl_add_u64 v[98:99], s[10:11], 0, v[98:99]
	s_waitcnt vmcnt(28)
	v_lshlrev_b32_e32 v108, 16, v214
	v_and_b32_e32 v109, 0xffff0000, v214
	v_lshlrev_b32_e32 v102, 16, v215
	v_and_b32_e32 v103, 0xffff0000, v215
	v_lshlrev_b32_e32 v110, 16, v216
	v_and_b32_e32 v111, 0xffff0000, v216
	v_lshlrev_b32_e32 v104, 16, v217
	v_and_b32_e32 v105, 0xffff0000, v217
	v_lshlrev_b32_e32 v112, 16, v218
	v_and_b32_e32 v113, 0xffff0000, v218
	v_lshlrev_b32_e32 v106, 16, v219
	v_and_b32_e32 v107, 0xffff0000, v219
	v_lshlrev_b32_e32 v116, 16, v220
	v_and_b32_e32 v117, 0xffff0000, v220
	v_lshlrev_b32_e32 v100, 16, v221
	v_and_b32_e32 v101, 0xffff0000, v221
	v_pk_add_f32 v[94:95], v[94:95], v[102:103]
	v_pk_add_f32 v[92:93], v[92:93], v[108:109]
	v_pk_add_f32 v[90:91], v[90:91], v[104:105]
	v_pk_add_f32 v[88:89], v[88:89], v[110:111]
	v_pk_add_f32 v[86:87], v[86:87], v[106:107]
	v_pk_add_f32 v[84:85], v[84:85], v[112:113]
	v_pk_add_f32 v[82:83], v[82:83], v[100:101]
	v_pk_add_f32 v[100:101], v[80:81], v[116:117]
	v_mul_f32_e32 v102, v93, v93
	v_mul_f32_e32 v103, v95, v95
	v_cvt_pk_bf16_f32 v80, v92, v93
	v_cvt_pk_bf16_f32 v81, v94, v95
	v_mul_f32_e32 v93, v89, v89
	v_mul_f32_e32 v95, v91, v91
	v_mul_f32_e32 v104, v85, v85
	v_mul_f32_e32 v105, v87, v87
	v_fmac_f32_e32 v102, v92, v92
	v_fmac_f32_e32 v103, v94, v94
	v_fmac_f32_e32 v93, v88, v88
	v_fmac_f32_e32 v95, v90, v90
	v_mul_f32_e32 v106, v101, v101
	v_mul_f32_e32 v107, v83, v83
	global_store_dwordx2 v[98:99], v[80:81], off
	v_cvt_pk_bf16_f32 v80, v88, v89
	v_fmac_f32_e32 v104, v84, v84
	v_fmac_f32_e32 v105, v86, v86
	v_add_f32_e32 v81, v102, v103
	v_add_f32_e32 v88, v93, v95
	v_fmac_f32_e32 v106, v100, v100
	v_fmac_f32_e32 v107, v82, v82
	v_add_f32_e32 v89, v104, v105
	v_add_f32_e32 v81, v81, v88
	v_add_f32_e32 v81, v81, v89
	v_add_f32_e32 v88, v106, v107
	v_add_f32_e32 v88, v81, v88
	ds_bpermute_b32 v89, v151, v88
	v_cvt_pk_bf16_f32 v81, v90, v91
	global_store_dwordx2 v[98:99], v[80:81], off offset:32
	v_cvt_pk_bf16_f32 v84, v84, v85
	v_cvt_pk_bf16_f32 v85, v86, v87
	s_waitcnt lgkmcnt(0)
	v_add_f32_e32 v80, v88, v89
	ds_bpermute_b32 v81, v114, v80
	global_store_dwordx2 v[98:99], v[84:85], off offset:256
	v_cvt_pk_bf16_f32 v84, v100, v101
	v_cvt_pk_bf16_f32 v85, v82, v83
	global_store_dwordx2 v[98:99], v[84:85], off offset:288
	s_and_saveexec_b64 s[54:55], s[0:1]
	s_cbranch_execz .LBB0_554
	v_lshlrev_b64 v[82:83], 7, v[96:97]
	v_lshl_add_u64 v[82:83], s[26:27], 0, v[82:83]
	v_lshl_add_u64 v[82:83], s[50:51], 2, v[82:83]
	s_lshl_b32 s12, s64, 2
	v_lshl_add_u64 v[82:83], v[82:83], 0, s[12:13]
	s_waitcnt lgkmcnt(0)
	v_add_f32_e32 v80, v80, v81
	global_store_dword v[82:83], v80, off
.LBB0_554:
	s_or_b64 exec, exec, s[54:55]
	v_or_b32_e32 v80, 48, v142
	s_waitcnt lgkmcnt(0)
	v_ashrrev_i32_e32 v81, 31, v80
	v_lshlrev_b64 v[82:83], 11, v[80:81]
	v_lshl_add_u64 v[82:83], v[82:83], 0, v[140:141]
	v_lshlrev_b64 v[82:83], 1, v[82:83]
	v_lshl_add_u64 v[84:85], s[18:19], 0, v[82:83]
	v_lshl_add_u64 v[82:83], s[10:11], 0, v[82:83]
	s_waitcnt vmcnt(28)
	v_lshlrev_b32_e32 v92, 16, v222
	v_and_b32_e32 v93, 0xffff0000, v222
	v_lshlrev_b32_e32 v86, 16, v223
	v_and_b32_e32 v87, 0xffff0000, v223
	v_lshlrev_b32_e32 v94, 16, v224
	v_and_b32_e32 v95, 0xffff0000, v224
	v_lshlrev_b32_e32 v88, 16, v225
	v_and_b32_e32 v89, 0xffff0000, v225
	v_lshlrev_b32_e32 v96, 16, v226
	v_and_b32_e32 v97, 0xffff0000, v226
	v_lshlrev_b32_e32 v90, 16, v227
	v_and_b32_e32 v91, 0xffff0000, v227
	v_lshlrev_b32_e32 v98, 16, v228
	v_and_b32_e32 v99, 0xffff0000, v228
	v_lshlrev_b32_e32 v84, 16, v229
	v_and_b32_e32 v85, 0xffff0000, v229
	v_pk_add_f32 v[78:79], v[78:79], v[86:87]
	v_pk_add_f32 v[76:77], v[76:77], v[92:93]
	v_pk_add_f32 v[74:75], v[74:75], v[88:89]
	v_pk_add_f32 v[72:73], v[72:73], v[94:95]
	v_pk_add_f32 v[70:71], v[70:71], v[90:91]
	v_pk_add_f32 v[68:69], v[68:69], v[96:97]
	v_pk_add_f32 v[66:67], v[66:67], v[84:85]
	v_pk_add_f32 v[84:85], v[64:65], v[98:99]
	v_mul_f32_e32 v86, v77, v77
	v_mul_f32_e32 v87, v79, v79
	v_cvt_pk_bf16_f32 v64, v76, v77
	v_cvt_pk_bf16_f32 v65, v78, v79
	v_mul_f32_e32 v77, v73, v73
	v_mul_f32_e32 v79, v75, v75
	v_mul_f32_e32 v88, v69, v69
	v_mul_f32_e32 v89, v71, v71
	v_fmac_f32_e32 v86, v76, v76
	v_fmac_f32_e32 v87, v78, v78
	v_fmac_f32_e32 v77, v72, v72
	v_fmac_f32_e32 v79, v74, v74
	v_mul_f32_e32 v90, v85, v85
	v_mul_f32_e32 v91, v67, v67
	global_store_dwordx2 v[82:83], v[64:65], off
	v_cvt_pk_bf16_f32 v64, v72, v73
	v_fmac_f32_e32 v88, v68, v68
	v_fmac_f32_e32 v89, v70, v70
	v_add_f32_e32 v65, v86, v87
	v_add_f32_e32 v72, v77, v79
	v_fmac_f32_e32 v90, v84, v84
	v_fmac_f32_e32 v91, v66, v66
	v_add_f32_e32 v73, v88, v89
	v_add_f32_e32 v65, v65, v72
	v_add_f32_e32 v65, v65, v73
	v_add_f32_e32 v72, v90, v91
	v_add_f32_e32 v72, v65, v72
	ds_bpermute_b32 v73, v151, v72
	v_cvt_pk_bf16_f32 v65, v74, v75
	global_store_dwordx2 v[82:83], v[64:65], off offset:32
	v_cvt_pk_bf16_f32 v68, v68, v69
	v_cvt_pk_bf16_f32 v69, v70, v71
	s_waitcnt lgkmcnt(0)
	v_add_f32_e32 v64, v72, v73
	ds_bpermute_b32 v65, v114, v64
	global_store_dwordx2 v[82:83], v[68:69], off offset:256
	v_cvt_pk_bf16_f32 v68, v84, v85
	v_cvt_pk_bf16_f32 v69, v66, v67
	global_store_dwordx2 v[82:83], v[68:69], off offset:288
	s_and_saveexec_b64 s[54:55], s[0:1]
	s_cbranch_execz .LBB0_556
	v_lshlrev_b64 v[66:67], 7, v[80:81]
	v_lshl_add_u64 v[66:67], s[26:27], 0, v[66:67]
	v_lshl_add_u64 v[66:67], s[50:51], 2, v[66:67]
	s_lshl_b32 s12, s64, 2
	v_lshl_add_u64 v[66:67], v[66:67], 0, s[12:13]
	s_waitcnt lgkmcnt(0)
	v_add_f32_e32 v64, v64, v65
	global_store_dword v[66:67], v64, off
.LBB0_556:
	s_or_b64 exec, exec, s[54:55]
	v_add_u32_e32 v64, 0x80, v142
	s_waitcnt lgkmcnt(0)
	v_ashrrev_i32_e32 v65, 31, v64
	v_lshlrev_b64 v[66:67], 11, v[64:65]
	v_lshl_add_u64 v[66:67], v[66:67], 0, v[140:141]
	v_lshlrev_b64 v[66:67], 1, v[66:67]
	v_lshl_add_u64 v[68:69], s[18:19], 0, v[66:67]
	v_lshl_add_u64 v[66:67], s[10:11], 0, v[66:67]
	s_waitcnt vmcnt(28)
	v_lshlrev_b32_e32 v76, 16, v230
	v_and_b32_e32 v77, 0xffff0000, v230
	v_lshlrev_b32_e32 v70, 16, v231
	v_and_b32_e32 v71, 0xffff0000, v231
	v_lshlrev_b32_e32 v78, 16, v232
	v_and_b32_e32 v79, 0xffff0000, v232
	v_lshlrev_b32_e32 v72, 16, v233
	v_and_b32_e32 v73, 0xffff0000, v233
	v_lshlrev_b32_e32 v80, 16, v234
	v_and_b32_e32 v81, 0xffff0000, v234
	v_lshlrev_b32_e32 v74, 16, v235
	v_and_b32_e32 v75, 0xffff0000, v235
	v_lshlrev_b32_e32 v82, 16, v136
	v_and_b32_e32 v83, 0xffff0000, v136
	v_lshlrev_b32_e32 v68, 16, v137
	v_and_b32_e32 v69, 0xffff0000, v137
	v_pk_add_f32 v[62:63], v[62:63], v[70:71]
	v_pk_add_f32 v[60:61], v[60:61], v[76:77]
	v_pk_add_f32 v[58:59], v[58:59], v[72:73]
	v_pk_add_f32 v[56:57], v[56:57], v[78:79]
	v_pk_add_f32 v[54:55], v[54:55], v[74:75]
	v_pk_add_f32 v[52:53], v[52:53], v[80:81]
	v_pk_add_f32 v[50:51], v[50:51], v[68:69]
	v_pk_add_f32 v[68:69], v[48:49], v[82:83]
	v_mul_f32_e32 v70, v61, v61
	v_mul_f32_e32 v71, v63, v63
	v_cvt_pk_bf16_f32 v48, v60, v61
	v_cvt_pk_bf16_f32 v49, v62, v63
	v_mul_f32_e32 v61, v57, v57
	v_mul_f32_e32 v63, v59, v59
	v_mul_f32_e32 v72, v53, v53
	v_mul_f32_e32 v73, v55, v55
	v_fmac_f32_e32 v70, v60, v60
	v_fmac_f32_e32 v71, v62, v62
	v_fmac_f32_e32 v61, v56, v56
	v_fmac_f32_e32 v63, v58, v58
	v_mul_f32_e32 v74, v69, v69
	v_mul_f32_e32 v75, v51, v51
	global_store_dwordx2 v[66:67], v[48:49], off
	v_cvt_pk_bf16_f32 v48, v56, v57
	v_fmac_f32_e32 v72, v52, v52
	v_fmac_f32_e32 v73, v54, v54
	v_add_f32_e32 v49, v70, v71
	v_add_f32_e32 v56, v61, v63
	v_fmac_f32_e32 v74, v68, v68
	v_fmac_f32_e32 v75, v50, v50
	v_add_f32_e32 v57, v72, v73
	v_add_f32_e32 v49, v49, v56
	v_add_f32_e32 v49, v49, v57
	v_add_f32_e32 v56, v74, v75
	v_add_f32_e32 v56, v49, v56
	ds_bpermute_b32 v57, v151, v56
	v_cvt_pk_bf16_f32 v49, v58, v59
	global_store_dwordx2 v[66:67], v[48:49], off offset:32
	v_cvt_pk_bf16_f32 v52, v52, v53
	v_cvt_pk_bf16_f32 v53, v54, v55
	s_waitcnt lgkmcnt(0)
	v_add_f32_e32 v48, v56, v57
	ds_bpermute_b32 v49, v114, v48
	global_store_dwordx2 v[66:67], v[52:53], off offset:256
	v_cvt_pk_bf16_f32 v52, v68, v69
	v_cvt_pk_bf16_f32 v53, v50, v51
	global_store_dwordx2 v[66:67], v[52:53], off offset:288
	s_and_saveexec_b64 s[54:55], s[0:1]
	s_cbranch_execz .LBB0_558
	v_lshlrev_b64 v[50:51], 7, v[64:65]
	v_lshl_add_u64 v[50:51], s[26:27], 0, v[50:51]
	v_lshl_add_u64 v[50:51], s[50:51], 2, v[50:51]
	s_lshl_b32 s12, s64, 2
	v_lshl_add_u64 v[50:51], v[50:51], 0, s[12:13]
	s_waitcnt lgkmcnt(0)
	v_add_f32_e32 v48, v48, v49
	global_store_dword v[50:51], v48, off
.LBB0_558:
	s_or_b64 exec, exec, s[54:55]
	v_add_u32_e32 v48, 0x90, v142
	s_waitcnt lgkmcnt(0)
	v_ashrrev_i32_e32 v49, 31, v48
	v_lshlrev_b64 v[50:51], 11, v[48:49]
	v_lshl_add_u64 v[50:51], v[50:51], 0, v[140:141]
	v_lshlrev_b64 v[50:51], 1, v[50:51]
	v_lshl_add_u64 v[52:53], s[18:19], 0, v[50:51]
	v_lshl_add_u64 v[50:51], s[10:11], 0, v[50:51]
	s_waitcnt vmcnt(28)
	v_lshlrev_b32_e32 v60, 16, v240
	v_and_b32_e32 v61, 0xffff0000, v240
	v_lshlrev_b32_e32 v54, 16, v241
	v_and_b32_e32 v55, 0xffff0000, v241
	v_lshlrev_b32_e32 v62, 16, v242
	v_and_b32_e32 v63, 0xffff0000, v242
	v_lshlrev_b32_e32 v56, 16, v243
	v_and_b32_e32 v57, 0xffff0000, v243
	v_lshlrev_b32_e32 v64, 16, v244
	v_and_b32_e32 v65, 0xffff0000, v244
	v_lshlrev_b32_e32 v58, 16, v245
	v_and_b32_e32 v59, 0xffff0000, v245
	v_lshlrev_b32_e32 v66, 16, v246
	v_and_b32_e32 v67, 0xffff0000, v246
	v_lshlrev_b32_e32 v52, 16, v247
	v_and_b32_e32 v53, 0xffff0000, v247
	v_pk_add_f32 v[46:47], v[46:47], v[54:55]
	v_pk_add_f32 v[44:45], v[44:45], v[60:61]
	v_pk_add_f32 v[42:43], v[42:43], v[56:57]
	v_pk_add_f32 v[40:41], v[40:41], v[62:63]
	v_pk_add_f32 v[38:39], v[38:39], v[58:59]
	v_pk_add_f32 v[36:37], v[36:37], v[64:65]
	v_pk_add_f32 v[34:35], v[34:35], v[52:53]
	v_pk_add_f32 v[52:53], v[32:33], v[66:67]
	v_mul_f32_e32 v54, v45, v45
	v_mul_f32_e32 v55, v47, v47
	v_cvt_pk_bf16_f32 v32, v44, v45
	v_cvt_pk_bf16_f32 v33, v46, v47
	v_mul_f32_e32 v45, v41, v41
	v_mul_f32_e32 v47, v43, v43
	v_mul_f32_e32 v56, v37, v37
	v_mul_f32_e32 v57, v39, v39
	v_fmac_f32_e32 v54, v44, v44
	v_fmac_f32_e32 v55, v46, v46
	v_fmac_f32_e32 v45, v40, v40
	v_fmac_f32_e32 v47, v42, v42
	v_mul_f32_e32 v58, v53, v53
	v_mul_f32_e32 v59, v35, v35
	global_store_dwordx2 v[50:51], v[32:33], off
	v_cvt_pk_bf16_f32 v32, v40, v41
	v_fmac_f32_e32 v56, v36, v36
	v_fmac_f32_e32 v57, v38, v38
	v_add_f32_e32 v33, v54, v55
	v_add_f32_e32 v40, v45, v47
	v_fmac_f32_e32 v58, v52, v52
	v_fmac_f32_e32 v59, v34, v34
	v_add_f32_e32 v41, v56, v57
	v_add_f32_e32 v33, v33, v40
	v_add_f32_e32 v33, v33, v41
	v_add_f32_e32 v40, v58, v59
	v_add_f32_e32 v40, v33, v40
	ds_bpermute_b32 v41, v151, v40
	v_cvt_pk_bf16_f32 v33, v42, v43
	global_store_dwordx2 v[50:51], v[32:33], off offset:32
	v_cvt_pk_bf16_f32 v36, v36, v37
	v_cvt_pk_bf16_f32 v37, v38, v39
	s_waitcnt lgkmcnt(0)
	v_add_f32_e32 v32, v40, v41
	ds_bpermute_b32 v33, v114, v32
	global_store_dwordx2 v[50:51], v[36:37], off offset:256
	v_cvt_pk_bf16_f32 v36, v52, v53
	v_cvt_pk_bf16_f32 v37, v34, v35
	global_store_dwordx2 v[50:51], v[36:37], off offset:288
	s_and_saveexec_b64 s[54:55], s[0:1]
	s_cbranch_execz .LBB0_560
	v_lshlrev_b64 v[34:35], 7, v[48:49]
	v_lshl_add_u64 v[34:35], s[26:27], 0, v[34:35]
	v_lshl_add_u64 v[34:35], s[50:51], 2, v[34:35]
	s_lshl_b32 s12, s64, 2
	v_lshl_add_u64 v[34:35], v[34:35], 0, s[12:13]
	s_waitcnt lgkmcnt(0)
	v_add_f32_e32 v32, v32, v33
	global_store_dword v[34:35], v32, off
.LBB0_560:
	s_or_b64 exec, exec, s[54:55]
	v_add_u32_e32 v32, 0xa0, v142
	s_waitcnt lgkmcnt(0)
	v_ashrrev_i32_e32 v33, 31, v32
	v_lshlrev_b64 v[34:35], 11, v[32:33]
	v_lshl_add_u64 v[34:35], v[34:35], 0, v[140:141]
	v_lshlrev_b64 v[34:35], 1, v[34:35]
	v_lshl_add_u64 v[36:37], s[18:19], 0, v[34:35]
	v_lshl_add_u64 v[34:35], s[10:11], 0, v[34:35]
	s_waitcnt vmcnt(28)
	v_lshlrev_b32_e32 v44, 16, v248
	v_and_b32_e32 v45, 0xffff0000, v248
	v_lshlrev_b32_e32 v38, 16, v249
	v_and_b32_e32 v39, 0xffff0000, v249
	v_lshlrev_b32_e32 v46, 16, v250
	v_and_b32_e32 v47, 0xffff0000, v250
	v_lshlrev_b32_e32 v40, 16, v251
	v_and_b32_e32 v41, 0xffff0000, v251
	v_lshlrev_b32_e32 v48, 16, v252
	v_and_b32_e32 v49, 0xffff0000, v252
	v_lshlrev_b32_e32 v42, 16, v253
	v_and_b32_e32 v43, 0xffff0000, v253
	v_lshlrev_b32_e32 v50, 16, v254
	v_and_b32_e32 v51, 0xffff0000, v254
	v_lshlrev_b32_e32 v36, 16, v255
	v_and_b32_e32 v37, 0xffff0000, v255
	v_pk_add_f32 v[30:31], v[30:31], v[38:39]
	v_pk_add_f32 v[28:29], v[28:29], v[44:45]
	v_pk_add_f32 v[26:27], v[26:27], v[40:41]
	v_pk_add_f32 v[24:25], v[24:25], v[46:47]
	v_pk_add_f32 v[22:23], v[22:23], v[42:43]
	v_pk_add_f32 v[20:21], v[20:21], v[48:49]
	v_pk_add_f32 v[18:19], v[18:19], v[36:37]
	v_pk_add_f32 v[36:37], v[16:17], v[50:51]
	v_mul_f32_e32 v38, v29, v29
	v_mul_f32_e32 v39, v31, v31
	v_cvt_pk_bf16_f32 v16, v28, v29
	v_cvt_pk_bf16_f32 v17, v30, v31
	v_mul_f32_e32 v29, v25, v25
	v_mul_f32_e32 v31, v27, v27
	v_mul_f32_e32 v40, v21, v21
	v_mul_f32_e32 v41, v23, v23
	v_fmac_f32_e32 v38, v28, v28
	v_fmac_f32_e32 v39, v30, v30
	v_fmac_f32_e32 v29, v24, v24
	v_fmac_f32_e32 v31, v26, v26
	v_mul_f32_e32 v42, v37, v37
	v_mul_f32_e32 v43, v19, v19
	global_store_dwordx2 v[34:35], v[16:17], off
	v_cvt_pk_bf16_f32 v16, v24, v25
	v_fmac_f32_e32 v40, v20, v20
	v_fmac_f32_e32 v41, v22, v22
	v_add_f32_e32 v17, v38, v39
	v_add_f32_e32 v24, v29, v31
	v_fmac_f32_e32 v42, v36, v36
	v_fmac_f32_e32 v43, v18, v18
	v_add_f32_e32 v25, v40, v41
	v_add_f32_e32 v17, v17, v24
	v_add_f32_e32 v17, v17, v25
	v_add_f32_e32 v24, v42, v43
	v_add_f32_e32 v24, v17, v24
	ds_bpermute_b32 v25, v151, v24
	v_cvt_pk_bf16_f32 v17, v26, v27
	global_store_dwordx2 v[34:35], v[16:17], off offset:32
	v_cvt_pk_bf16_f32 v20, v20, v21
	v_cvt_pk_bf16_f32 v21, v22, v23
	s_waitcnt lgkmcnt(0)
	v_add_f32_e32 v16, v24, v25
	ds_bpermute_b32 v17, v114, v16
	global_store_dwordx2 v[34:35], v[20:21], off offset:256
	v_cvt_pk_bf16_f32 v20, v36, v37
	v_cvt_pk_bf16_f32 v21, v18, v19
	global_store_dwordx2 v[34:35], v[20:21], off offset:288
	s_and_saveexec_b64 s[54:55], s[0:1]
	s_cbranch_execz .LBB0_562
	v_lshlrev_b64 v[18:19], 7, v[32:33]
	v_lshl_add_u64 v[18:19], s[26:27], 0, v[18:19]
	v_lshl_add_u64 v[18:19], s[50:51], 2, v[18:19]
	s_lshl_b32 s12, s64, 2
	v_lshl_add_u64 v[18:19], v[18:19], 0, s[12:13]
	s_waitcnt lgkmcnt(0)
	v_add_f32_e32 v16, v16, v17
	global_store_dword v[18:19], v16, off
.LBB0_562:
	s_or_b64 exec, exec, s[54:55]
	v_add_u32_e32 v16, 0xb0, v142
	s_waitcnt lgkmcnt(0)
	v_ashrrev_i32_e32 v17, 31, v16
	v_lshlrev_b64 v[18:19], 11, v[16:17]
	v_lshl_add_u64 v[18:19], v[18:19], 0, v[140:141]
	v_lshlrev_b64 v[18:19], 1, v[18:19]
	v_lshl_add_u64 v[20:21], s[18:19], 0, v[18:19]
	v_lshl_add_u64 v[18:19], s[10:11], 0, v[18:19]
	s_waitcnt vmcnt(20)
	v_lshlrev_b32_e32 v28, 16, v128
	v_and_b32_e32 v29, 0xffff0000, v128
	v_lshlrev_b32_e32 v22, 16, v129
	v_and_b32_e32 v23, 0xffff0000, v129
	v_lshlrev_b32_e32 v30, 16, v130
	v_and_b32_e32 v31, 0xffff0000, v130
	v_lshlrev_b32_e32 v24, 16, v131
	v_and_b32_e32 v25, 0xffff0000, v131
	v_lshlrev_b32_e32 v32, 16, v132
	v_and_b32_e32 v33, 0xffff0000, v132
	v_lshlrev_b32_e32 v26, 16, v133
	v_and_b32_e32 v27, 0xffff0000, v133
	v_lshlrev_b32_e32 v34, 16, v134
	v_and_b32_e32 v35, 0xffff0000, v134
	v_lshlrev_b32_e32 v20, 16, v135
	v_and_b32_e32 v21, 0xffff0000, v135
	v_pk_add_f32 v[14:15], v[14:15], v[22:23]
	v_pk_add_f32 v[12:13], v[12:13], v[28:29]
	v_pk_add_f32 v[10:11], v[10:11], v[24:25]
	v_pk_add_f32 v[8:9], v[8:9], v[30:31]
	v_pk_add_f32 v[6:7], v[6:7], v[26:27]
	v_pk_add_f32 v[4:5], v[4:5], v[32:33]
	v_pk_add_f32 v[2:3], v[2:3], v[20:21]
	v_pk_add_f32 v[20:21], v[0:1], v[34:35]
	v_mul_f32_e32 v22, v13, v13
	v_mul_f32_e32 v23, v15, v15
	v_cvt_pk_bf16_f32 v0, v12, v13
	v_cvt_pk_bf16_f32 v1, v14, v15
	v_mul_f32_e32 v13, v9, v9
	v_mul_f32_e32 v15, v11, v11
	v_mul_f32_e32 v24, v5, v5
	v_mul_f32_e32 v25, v7, v7
	v_fmac_f32_e32 v22, v12, v12
	v_fmac_f32_e32 v23, v14, v14
	v_fmac_f32_e32 v13, v8, v8
	v_fmac_f32_e32 v15, v10, v10
	v_mul_f32_e32 v26, v21, v21
	v_mul_f32_e32 v27, v3, v3
	global_store_dwordx2 v[18:19], v[0:1], off
	v_cvt_pk_bf16_f32 v0, v8, v9
	v_fmac_f32_e32 v24, v4, v4
	v_fmac_f32_e32 v25, v6, v6
	v_add_f32_e32 v1, v22, v23
	v_add_f32_e32 v8, v13, v15
	v_fmac_f32_e32 v26, v20, v20
	v_fmac_f32_e32 v27, v2, v2
	v_add_f32_e32 v9, v24, v25
	v_add_f32_e32 v1, v1, v8
	v_add_f32_e32 v1, v1, v9
	v_add_f32_e32 v8, v26, v27
	v_add_f32_e32 v8, v1, v8
	ds_bpermute_b32 v9, v151, v8
	v_cvt_pk_bf16_f32 v1, v10, v11
	global_store_dwordx2 v[18:19], v[0:1], off offset:32
	v_cvt_pk_bf16_f32 v4, v4, v5
	v_cvt_pk_bf16_f32 v5, v6, v7
	s_waitcnt lgkmcnt(0)
	v_add_f32_e32 v0, v8, v9
	ds_bpermute_b32 v1, v114, v0
	global_store_dwordx2 v[18:19], v[4:5], off offset:256
	v_cvt_pk_bf16_f32 v4, v20, v21
	v_cvt_pk_bf16_f32 v5, v2, v3
	global_store_dwordx2 v[18:19], v[4:5], off offset:288
	s_and_saveexec_b64 s[54:55], s[0:1]
	s_cbranch_execz .LBB0_564
	v_lshlrev_b64 v[2:3], 7, v[16:17]
	v_lshl_add_u64 v[2:3], s[26:27], 0, v[2:3]
	v_lshl_add_u64 v[2:3], s[50:51], 2, v[2:3]
	s_lshl_b32 s12, s64, 2
	v_lshl_add_u64 v[2:3], v[2:3], 0, s[12:13]
	s_waitcnt lgkmcnt(0)
	v_add_f32_e32 v0, v0, v1
	global_store_dword v[2:3], v0, off

	.amdhsa_kernel _Z9block_fwd4Args
		.amdhsa_group_segment_fixed_size 0
		.amdhsa_private_segment_fixed_size 0
		.amdhsa_kernarg_size 408
		.amdhsa_user_sgpr_count 2
		.amdhsa_user_sgpr_dispatch_ptr 0
		.amdhsa_user_sgpr_queue_ptr 0
		.amdhsa_user_sgpr_kernarg_segment_ptr 1
		.amdhsa_user_sgpr_dispatch_id 0
		.amdhsa_user_sgpr_kernarg_preload_length 0
		.amdhsa_user_sgpr_kernarg_preload_offset 0
		.amdhsa_user_sgpr_private_segment_size 0
		.amdhsa_uses_dynamic_stack 0
		.amdhsa_enable_private_segment 0
		.amdhsa_system_sgpr_workgroup_id_x 1
		.amdhsa_system_sgpr_workgroup_id_y 0
		.amdhsa_system_sgpr_workgroup_id_z 0
		.amdhsa_system_sgpr_workgroup_info 0
		.amdhsa_system_vgpr_workitem_id 2
		.amdhsa_next_free_vgpr 256
		.amdhsa_next_free_sgpr 102
		.amdhsa_accum_offset 256
		.amdhsa_reserve_vcc 1
		.amdhsa_float_round_mode_32 0
		.amdhsa_float_round_mode_16_64 0
		.amdhsa_float_denorm_mode_32 3
		.amdhsa_float_denorm_mode_16_64 3
		.amdhsa_dx10_clamp 1
		.amdhsa_ieee_mode 1
		.amdhsa_fp16_overflow 0
		.amdhsa_tg_split 0
		.amdhsa_exception_fp_ieee_invalid_op 0
		.amdhsa_exception_fp_denorm_src 0
		.amdhsa_exception_fp_ieee_div_zero 0
		.amdhsa_exception_fp_ieee_overflow 0
		.amdhsa_exception_fp_ieee_underflow 0
		.amdhsa_exception_fp_ieee_inexact 0
		.amdhsa_exception_int_div_zero 0
	.end_amdhsa_kernel

amdhsa.kernels:
  - .agpr_count:     0
    .args:
      - .offset:         0
        .size:           152
        .value_kind:     by_value
      - .offset:         152
        .size:           4
        .value_kind:     hidden_block_count_x
      - .offset:         156
        .size:           4
        .value_kind:     hidden_block_count_y
      - .offset:         160
        .size:           4
        .value_kind:     hidden_block_count_z
      - .offset:         164
        .size:           2
        .value_kind:     hidden_group_size_x
      - .offset:         166
        .size:           2
        .value_kind:     hidden_group_size_y
      - .offset:         168
        .size:           2
        .value_kind:     hidden_group_size_z
      - .offset:         170
        .size:           2
        .value_kind:     hidden_remainder_x
      - .offset:         172
        .size:           2
        .value_kind:     hidden_remainder_y
      - .offset:         174
        .size:           2
        .value_kind:     hidden_remainder_z
      - .offset:         192
        .size:           8
        .value_kind:     hidden_global_offset_x
      - .offset:         200
        .size:           8
        .value_kind:     hidden_global_offset_y
      - .offset:         208
        .size:           8
        .value_kind:     hidden_global_offset_z
      - .offset:         216
        .size:           2
        .value_kind:     hidden_grid_dims
      - .offset:         240
        .size:           8
        .value_kind:     hidden_multigrid_sync_arg
      - .offset:         272
        .size:           4
        .value_kind:     hidden_dynamic_lds_size
    .group_segment_fixed_size: 0
    .kernarg_segment_align: 8
    .kernarg_segment_size: 408
    .language:       OpenCL C
    .language_version:
      - 2
      - 0
    .max_flat_workgroup_size: 512
    .name:           _Z9block_fwd4Args
    .private_segment_fixed_size: 0
    .sgpr_count:     108
    .sgpr_spill_count: 5
    .symbol:         _Z9block_fwd4Args.kd
    .uniform_work_group_size: 1
    .uses_dynamic_stack: false
    .vgpr_count:     256
    .vgpr_spill_count: 0
    .wavefront_size: 64
